# prep: lora-weight tile transposes load 16 rows in flight (was a 2-deep vectorised loop)
# baseline (speedup 1.0000x reference)
.LBB0_65:
	s_add_i32 s4, s37, 0xfffffcb0
	s_and_b32 s11, s37, 15
	v_mov_b32_e32 v2, v172
	s_cmp_lt_u32 s4, 32
	s_cselect_b64 s[6:7], -1, 0
	v_max_i32_e32 v0, 0xf00, v2
	s_bfe_u32 s38, s4, 0x10004
	v_cmp_gt_i32_e32 vcc, s26, v2
	v_sub_u32_e32 v8, v0, v2
	s_and_saveexec_b64 s[18:19], vcc
	s_cbranch_execz .LBB0_78
	s_load_dwordx16 s[56:71], s[0:1], 0x80
	s_and_b64 s[4:5], s[6:7], exec
	v_lshlrev_b32_e32 v0, 2, v2
	v_and_b32_e32 v0, 0xfc, v0
	v_add_u32_e32 v6, 0xff, v8
	s_waitcnt lgkmcnt(0)
	s_cselect_b32 s20, s59, s65
	s_cselect_b32 s21, s58, s64
	s_lshl_b32 s4, s10, 1
	s_or_b32 s4, s38, s4
	s_ashr_i32 s5, s4, 31
	s_lshl_b64 s[4:5], s[4:5], 18
	s_add_u32 s4, s21, s4
	s_addc_u32 s5, s20, s5
	s_lshl_b32 s39, s11, 6
	v_lshl_add_u64 v[4:5], s[4:5], 0, v[0:1]
	v_lshrrev_b32_e32 v9, 6, v2
	v_add_u32_e32 v6, s39, v9
	v_ashrrev_i32_e32 v7, 31, v6
	v_lshlrev_b64 v[6:7], 8, v[6:7]
	v_lshl_add_u64 v[6:7], v[4:5], 0, v[6:7]
	v_mad_u64_u32 v[14:15], s[4:5], v9, s28, v[0:1]
	s_mov_b64 s[4:5], 0x1000
	global_load_dword v58, v[6:7], off
	global_load_dword v59, v[6:7], off offset:1024
	global_load_dword v60, v[6:7], off offset:2048
	global_load_dword v61, v[6:7], off offset:3072
	v_lshl_add_u64 v[16:17], v[6:7], 0, s[4:5]
	global_load_dword v62, v[16:17], off
	global_load_dword v63, v[16:17], off offset:1024
	global_load_dword v64, v[16:17], off offset:2048
	global_load_dword v65, v[16:17], off offset:3072
	v_lshl_add_u64 v[6:7], v[16:17], 0, s[4:5]
	global_load_dword v66, v[6:7], off
	global_load_dword v67, v[6:7], off offset:1024
	global_load_dword v68, v[6:7], off offset:2048
	global_load_dword v69, v[6:7], off offset:3072
	v_lshl_add_u64 v[16:17], v[6:7], 0, s[4:5]
	global_load_dword v70, v[16:17], off
	global_load_dword v71, v[16:17], off offset:1024
	global_load_dword v72, v[16:17], off offset:2048
	global_load_dword v73, v[16:17], off offset:3072
	s_waitcnt vmcnt(15)
	ds_write_b32 v14, v58
	s_waitcnt vmcnt(14)
	ds_write_b32 v14, v59 offset:1040
	s_waitcnt vmcnt(13)
	ds_write_b32 v14, v60 offset:2080
	s_waitcnt vmcnt(12)
	ds_write_b32 v14, v61 offset:3120
	s_waitcnt vmcnt(11)
	ds_write_b32 v14, v62 offset:4160
	s_waitcnt vmcnt(10)
	ds_write_b32 v14, v63 offset:5200
	s_waitcnt vmcnt(9)
	ds_write_b32 v14, v64 offset:6240
	s_waitcnt vmcnt(8)
	ds_write_b32 v14, v65 offset:7280
	s_waitcnt vmcnt(7)
	ds_write_b32 v14, v66 offset:8320
	s_waitcnt vmcnt(6)
	ds_write_b32 v14, v67 offset:9360
	s_waitcnt vmcnt(5)
	ds_write_b32 v14, v68 offset:10400
	s_waitcnt vmcnt(4)
	ds_write_b32 v14, v69 offset:11440
	s_waitcnt vmcnt(3)
	ds_write_b32 v14, v70 offset:12480
	s_waitcnt vmcnt(2)
	ds_write_b32 v14, v71 offset:13520
	s_waitcnt vmcnt(1)
	ds_write_b32 v14, v72 offset:14560
	s_waitcnt vmcnt(0)
	ds_write_b32 v14, v73 offset:15600
